# MLA loop: back edge rotated out of the loop head (7.11): the loop-back barrier is the loop's first instruction, the branch is taken before it, exit path has its own barrier
# speedup vs baseline: 1.0048x; 1.0048x over previous
; template <int MODE>
; DI void attn_item(const Params& p, int layer, int bh, int qb, char* lds) {
;     ...
;         for (int sub = 0; sub < 2; ++sub) {
; #pragma unroll
;           for (int st = 0; st < QS; ++st) {
;             bf16x8 kf = *(const bf16x8*)(Ks + (32 * sub + l32) * KSTR + ((mp * QS + st) * 16 + hh * 8) * 2);
;             if (st == 0) s[sub] = MFMA(kf, qf[mp][st], c0tile); else s[sub] = MFMA(kf, qf[mp][st], s[sub]);
;           }
;         }
;         __builtin_amdgcn_iglp_opt(1);
;         __builtin_amdgcn_s_setprio(0);
;         if (NMAP == 1) {
;           lds_s16x4* vb = (lds_s16x4*)(Ks + KBYTES + vlane);
; #pragma unroll
;           for (int i = 0; i < 16; ++i) {
;             const int sub_ = i >> 3, ks_ = (i >> 2) & 1, dt_ = (i >> 1) & 1, g_ = i & 1;
;             vpre[i] = __builtin_amdgcn_ds_read_tr16_b64_v4i16(vb + ((32 * sub_ + 16 * ks_ + 8 * g_) * VSTR + 64 * dt_) / 8);
;           }
;           __builtin_amdgcn_sched_barrier(0);
;         }
;         if (MODE != 0 && !far) {
; #pragma unroll
;           for (int sub = 0; sub < 2; ++sub)
; #pragma unroll
;             for (int r = 0; r < 16; ++r) s[sub][r] += brow[32 * sub + (r & 3) + 8 * (r >> 2)];
;         }
;         const bool first = (MODE != 2) && (t == 0) && (mp == 0);
;         auto rebase = [&]() {
;           float mx = fmaxf(fmaxf(s[0][0], s[0][1]), s[0][2]);
; #pragma unroll
;           for (int r = 3; r < 15; r += 2) mx = fmaxf(fmaxf(mx, s[0][r]), s[0][r + 1]);
;           mx = fmaxf(mx, s[0][15]);
; #pragma unroll
;           for (int r = 0; r < 16; r += 2) mx = fmaxf(fmaxf(mx, s[1][r]), s[1][r + 1]);
;           const float rm = xchg_max(mx);
;           float delta = first ? rm : fmaxf(rm, 0.f);
;           if (delta < -1e29f) delta = 0.f;
;           m += delta;
;           const float alpha = __builtin_amdgcn_exp2f(-delta);
; #pragma unroll
;           for (int mq = 0; mq < NMAP; ++mq) {
;             l[mq] *= alpha;
; #pragma unroll
;             for (int r = 0; r < 16; ++r) { O[mq][0][r] *= alpha; O[mq][1][r] *= alpha; }
;           }
; #pragma unroll
;           for (int r = 0; r < 16; ++r) { s[0][r] -= delta; s[1][r] -= delta; }
;           set_c0(cb - m);
;         };
;         float ps;
;         auto smpass = [&]() {
;           ps = 0.f;
; #pragma unroll
;           for (int sub = 0; sub < 2; ++sub)
; #pragma unroll
;             for (int ks = 0; ks < 2; ++ks)
.Lmla_loop:
	s_barrier
	ds_read_b128 v[176:179], v200 offset:27648
	ds_read_b128 v[180:183], v200 offset:27680
	ds_read_b128 v[222:225], v200 offset:27712
	s_waitcnt vmcnt(3)
	ds_write_b128 v202, v[96:99] offset:2048
	ds_write_b64 v203, v[100:101] offset:2048
	ds_write_b128 v207, v[188:191] offset:40960
	buffer_load_dwordx4 v[96:99], v187, s[20:23], s62 offen
	buffer_load_dwordx2 v[100:101], v205, s[20:23], s62 offen
	buffer_load_dwordx4 v[188:191], v187, s[12:15], s29 offen
	s_add_u32 s62, s62, 0x3000
	s_add_u32 s29, s29, 0x2000
	v_exp_f32_e32 v0, v64
	v_exp_f32_e32 v1, v65
	v_exp_f32_e32 v2, v66
	v_exp_f32_e32 v3, v67
	v_add_f32_e32 v10, v0, v1
	v_cvt_pk_bf16_f32 v160, v0, v1
	s_waitcnt lgkmcnt(5)
	v_mfma_f32_32x32x16_bf16 v[128:143], v[176:179], v[104:107], v[48:63]
	ds_read_b128 v[226:229], v200 offset:27744
	s_waitcnt lgkmcnt(5)
	v_mfma_f32_32x32x16_bf16 v[128:143], v[180:183], v[108:111], v[128:143]
	ds_read_b64_tr_b16 v[176:177], v201 offset:15360
	ds_read_b64_tr_b16 v[178:179], v201 offset:16896
	v_add_f32_e32 v10, v10, v2
	v_add_f32_e32 v10, v10, v3
	v_cvt_pk_bf16_f32 v161, v2, v3
	s_waitcnt lgkmcnt(6)
	v_mfma_f32_32x32x16_bf16 v[128:143], v[222:225], v[112:115], v[128:143]
	ds_read_b64_tr_b16 v[180:181], v201 offset:15424
	ds_read_b64_tr_b16 v[182:183], v201 offset:16960
	v_exp_f32_e32 v6, v68
	v_exp_f32_e32 v7, v69
	v_exp_f32_e32 v8, v70
	v_exp_f32_e32 v9, v71
	v_add_f32_e32 v10, v10, v6
	s_waitcnt lgkmcnt(4)
	v_mfma_f32_32x32x16_bf16 v[128:143], v[226:229], v[116:119], v[128:143]
	ds_read_b128 v[222:225], v200 offset:27776
	v_add_f32_e32 v10, v10, v7
	v_cvt_pk_bf16_f32 v162, v6, v7
	v_add_f32_e32 v10, v10, v8
	v_add_f32_e32 v10, v10, v9
	v_cvt_pk_bf16_f32 v163, v8, v9
	s_waitcnt lgkmcnt(3)
	s_nop 0
	v_mfma_f32_32x32x16_bf16 v[32:47], v[176:179], v[160:163], v[32:47]
	ds_read_b128 v[226:229], v200 offset:27808
	v_exp_f32_e32 v0, v72
	v_exp_f32_e32 v1, v73
	v_exp_f32_e32 v2, v74
	s_waitcnt lgkmcnt(2)
	v_mfma_f32_32x32x16_bf16 v[16:31], v[180:183], v[160:163], v[16:31]
	ds_read_b128 v[176:179], v200 offset:34304
	v_exp_f32_e32 v3, v75
	v_add_f32_e32 v11, v0, v1
	v_cvt_pk_bf16_f32 v164, v0, v1
	v_add_f32_e32 v11, v11, v2
	s_waitcnt lgkmcnt(2)
	v_mfma_f32_32x32x16_bf16 v[128:143], v[222:225], v[120:123], v[128:143]
	ds_read_b64_tr_b16 v[180:181], v201 offset:18432
	ds_read_b64_tr_b16 v[182:183], v201 offset:19968
	v_add_f32_e32 v11, v11, v3
	v_cvt_pk_bf16_f32 v165, v2, v3
	v_exp_f32_e32 v6, v76
	v_exp_f32_e32 v7, v77
	s_waitcnt lgkmcnt(3)
	v_mfma_f32_32x32x16_bf16 v[128:143], v[226:229], v[124:127], v[128:143]
	ds_read_b64_tr_b16 v[222:223], v201 offset:18496
	ds_read_b64_tr_b16 v[224:225], v201 offset:20032
	v_exp_f32_e32 v8, v78
	v_exp_f32_e32 v9, v79
	v_add_f32_e32 v11, v11, v6
	v_add_f32_e32 v11, v11, v7
	s_waitcnt lgkmcnt(4)
	v_mfma_f32_32x32x16_bf16 v[144:159], v[176:179], v[104:107], v[48:63]
	ds_read_b128 v[226:229], v200 offset:34336
	v_cvt_pk_bf16_f32 v166, v6, v7
	v_add_f32_e32 v11, v11, v8
	v_add_f32_e32 v11, v11, v9
	v_cvt_pk_bf16_f32 v167, v8, v9
	s_waitcnt lgkmcnt(3)
	s_nop 0
	v_mfma_f32_32x32x16_bf16 v[32:47], v[180:183], v[164:167], v[32:47]
	ds_read_b128 v[176:179], v200 offset:34368
	v_exp_f32_e32 v0, v80
	v_exp_f32_e32 v1, v81
	v_exp_f32_e32 v2, v82
	s_waitcnt lgkmcnt(2)
	v_mfma_f32_32x32x16_bf16 v[16:31], v[222:225], v[164:167], v[16:31]
	ds_read_b128 v[180:183], v200 offset:34400
	v_exp_f32_e32 v3, v83
	v_add_f32_e32 v12, v0, v1
	v_cvt_pk_bf16_f32 v168, v0, v1
	v_add_f32_e32 v12, v12, v2
	s_waitcnt lgkmcnt(2)
	v_mfma_f32_32x32x16_bf16 v[144:159], v[226:229], v[108:111], v[144:159]
	ds_read_b64_tr_b16 v[222:223], v201 offset:21504
	ds_read_b64_tr_b16 v[224:225], v201 offset:23040
	v_add_f32_e32 v12, v12, v3
	v_cvt_pk_bf16_f32 v169, v2, v3
	v_exp_f32_e32 v6, v84
	v_exp_f32_e32 v7, v85
	s_waitcnt lgkmcnt(3)
	v_mfma_f32_32x32x16_bf16 v[144:159], v[176:179], v[112:115], v[144:159]
	ds_read_b64_tr_b16 v[226:227], v201 offset:21568
	ds_read_b64_tr_b16 v[228:229], v201 offset:23104
	v_exp_f32_e32 v8, v86
	v_exp_f32_e32 v9, v87
	v_add_f32_e32 v12, v12, v6
	v_add_f32_e32 v12, v12, v7
	s_waitcnt lgkmcnt(4)
	v_mfma_f32_32x32x16_bf16 v[144:159], v[180:183], v[116:119], v[144:159]
	ds_read_b128 v[176:179], v200 offset:34432
	v_cvt_pk_bf16_f32 v170, v6, v7
	v_add_f32_e32 v12, v12, v8
	v_add_f32_e32 v12, v12, v9
	v_cvt_pk_bf16_f32 v171, v8, v9
	s_waitcnt lgkmcnt(3)
	s_nop 0
	v_mfma_f32_32x32x16_bf16 v[32:47], v[222:225], v[168:171], v[32:47]
	ds_read_b128 v[180:183], v200 offset:34464
	v_exp_f32_e32 v0, v88
	v_exp_f32_e32 v1, v89
	v_exp_f32_e32 v2, v90
	v_exp_f32_e32 v3, v91
	s_waitcnt lgkmcnt(2)
	v_mfma_f32_32x32x16_bf16 v[16:31], v[226:229], v[168:171], v[16:31]
	ds_read_b64_tr_b16 v[222:223], v201 offset:24576
	ds_read_b64_tr_b16 v[224:225], v201 offset:26112
	v_add_f32_e32 v13, v0, v1
	v_cvt_pk_bf16_f32 v172, v0, v1
	v_add_f32_e32 v13, v13, v2
	v_add_f32_e32 v13, v13, v3
	v_cvt_pk_bf16_f32 v173, v2, v3
	s_waitcnt lgkmcnt(3)
	v_mfma_f32_32x32x16_bf16 v[144:159], v[176:179], v[120:123], v[144:159]
	ds_read_b64_tr_b16 v[226:227], v201 offset:24640
	ds_read_b64_tr_b16 v[228:229], v201 offset:26176
	v_exp_f32_e32 v6, v92
	v_exp_f32_e32 v7, v93
	v_exp_f32_e32 v8, v94
	v_exp_f32_e32 v9, v95
	v_add_f32_e32 v13, v13, v6
	s_waitcnt lgkmcnt(4)
	v_mfma_f32_32x32x16_bf16 v[144:159], v[180:183], v[124:127], v[144:159]
	v_add_f32_e32 v13, v13, v7
	v_cvt_pk_bf16_f32 v174, v6, v7
	v_add_f32_e32 v13, v13, v8
	v_add_f32_e32 v13, v13, v9
	v_cvt_pk_bf16_f32 v175, v8, v9
	s_waitcnt lgkmcnt(2)
	s_nop 0
	v_mfma_f32_32x32x16_bf16 v[32:47], v[222:225], v[172:175], v[32:47]
	s_waitcnt lgkmcnt(0)
	v_mfma_f32_32x32x16_bf16 v[16:31], v[226:229], v[172:175], v[16:31]
	v_add_f32_e32 v10, v10, v11
	v_add_f32_e32 v12, v12, v13
	v_add_f32_e32 v10, v10, v12
	v_add_f32_e32 v192, v192, v10
	v_max_f32_e32 v193, v193, v10
	s_waitcnt lgkmcnt(0)
	s_barrier
; template <int MODE>
; DI void attn_item(const Params& p, int layer, int bh, int qb, char* lds) {
;     ...
;         for (int sub = 0; sub < 2; ++sub) {
; #pragma unroll
;           for (int st = 0; st < QS; ++st) {
;             bf16x8 kf = *(const bf16x8*)(Ks + (32 * sub + l32) * KSTR + ((mp * QS + st) * 16 + hh * 8) * 2);
;             if (st == 0) s[sub] = MFMA(kf, qf[mp][st], c0tile); else s[sub] = MFMA(kf, qf[mp][st], s[sub]);
;           }
;         }
;         __builtin_amdgcn_iglp_opt(1);
;         __builtin_amdgcn_s_setprio(0);
;         if (NMAP == 1) {
;           lds_s16x4* vb = (lds_s16x4*)(Ks + KBYTES + vlane);
; #pragma unroll
;           for (int i = 0; i < 16; ++i) {
;             const int sub_ = i >> 3, ks_ = (i >> 2) & 1, dt_ = (i >> 1) & 1, g_ = i & 1;
;             vpre[i] = __builtin_amdgcn_ds_read_tr16_b64_v4i16(vb + ((32 * sub_ + 16 * ks_ + 8 * g_) * VSTR + 64 * dt_) / 8);
;           }
;           __builtin_amdgcn_sched_barrier(0);
;         }
;         if (MODE != 0 && !far) {
; #pragma unroll
;           for (int sub = 0; sub < 2; ++sub)
; #pragma unroll
;             for (int r = 0; r < 16; ++r) s[sub][r] += brow[32 * sub + (r & 3) + 8 * (r >> 2)];
;         }
;         const bool first = (MODE != 2) && (t == 0) && (mp == 0);
;         auto rebase = [&]() {
;           float mx = fmaxf(fmaxf(s[0][0], s[0][1]), s[0][2]);
; #pragma unroll
;           for (int r = 3; r < 15; r += 2) mx = fmaxf(fmaxf(mx, s[0][r]), s[0][r + 1]);
;           mx = fmaxf(mx, s[0][15]);
; #pragma unroll
;           for (int r = 0; r < 16; r += 2) mx = fmaxf(fmaxf(mx, s[1][r]), s[1][r + 1]);
;           const float rm = xchg_max(mx);
;           float delta = first ? rm : fmaxf(rm, 0.f);
;           if (delta < -1e29f) delta = 0.f;
;           m += delta;
;           const float alpha = __builtin_amdgcn_exp2f(-delta);
; #pragma unroll
;           for (int mq = 0; mq < NMAP; ++mq) {
;             l[mq] *= alpha;
; #pragma unroll
;             for (int r = 0; r < 16; ++r) { O[mq][0][r] *= alpha; O[mq][1][r] *= alpha; }
;           }
; #pragma unroll
;           for (int r = 0; r < 16; ++r) { s[0][r] -= delta; s[1][r] -= delta; }
;           set_c0(cb - m);
;         };
;         float ps;
;         auto smpass = [&]() {
;           ps = 0.f;
; #pragma unroll
;           for (int sub = 0; sub < 2; ++sub)
; #pragma unroll
;             for (int ks = 0; ks < 2; ++ks)
	ds_read_b128 v[176:179], v200 offset:2048
	ds_read_b128 v[180:183], v200 offset:2080
	ds_read_b128 v[222:225], v200 offset:2112
	s_waitcnt vmcnt(3)
	ds_write_b128 v202, v[230:233] offset:27648
	ds_write_b64 v203, v[234:235] offset:27648
	ds_write_b128 v207, v[236:239] offset:15360
	buffer_load_dwordx4 v[230:233], v187, s[20:23], s62 offen
	buffer_load_dwordx2 v[234:235], v205, s[20:23], s62 offen
	buffer_load_dwordx4 v[236:239], v187, s[12:15], s29 offen
	s_add_u32 s62, s62, 0x3000
	s_add_u32 s29, s29, 0x2000
	v_exp_f32_e32 v0, v128
	v_exp_f32_e32 v1, v129
	v_exp_f32_e32 v2, v130
	v_exp_f32_e32 v3, v131
	v_add_f32_e32 v10, v0, v1
	v_cvt_pk_bf16_f32 v160, v0, v1
	s_waitcnt lgkmcnt(5)
	v_mfma_f32_32x32x16_bf16 v[64:79], v[176:179], v[104:107], v[48:63]
	ds_read_b128 v[226:229], v200 offset:2144
	s_waitcnt lgkmcnt(5)
	v_mfma_f32_32x32x16_bf16 v[64:79], v[180:183], v[108:111], v[64:79]
	ds_read_b64_tr_b16 v[176:177], v201 offset:40960
	ds_read_b64_tr_b16 v[178:179], v201 offset:42496
	v_add_f32_e32 v10, v10, v2
	v_add_f32_e32 v10, v10, v3
	v_cvt_pk_bf16_f32 v161, v2, v3
	s_waitcnt lgkmcnt(6)
	v_mfma_f32_32x32x16_bf16 v[64:79], v[222:225], v[112:115], v[64:79]
	ds_read_b64_tr_b16 v[180:181], v201 offset:41024
	ds_read_b64_tr_b16 v[182:183], v201 offset:42560
	v_exp_f32_e32 v6, v132
	v_exp_f32_e32 v7, v133
	v_exp_f32_e32 v8, v134
	v_exp_f32_e32 v9, v135
	v_add_f32_e32 v10, v10, v6
	s_waitcnt lgkmcnt(4)
	v_mfma_f32_32x32x16_bf16 v[64:79], v[226:229], v[116:119], v[64:79]
	ds_read_b128 v[222:225], v200 offset:2176
	v_add_f32_e32 v10, v10, v7
	v_cvt_pk_bf16_f32 v162, v6, v7
	v_add_f32_e32 v10, v10, v8
	v_add_f32_e32 v10, v10, v9
	v_cvt_pk_bf16_f32 v163, v8, v9
	s_waitcnt lgkmcnt(3)
	s_nop 0
	v_mfma_f32_32x32x16_bf16 v[32:47], v[176:179], v[160:163], v[32:47]
	ds_read_b128 v[226:229], v200 offset:2208
	v_exp_f32_e32 v0, v136
	v_exp_f32_e32 v1, v137
	v_exp_f32_e32 v2, v138
	s_waitcnt lgkmcnt(2)
	v_mfma_f32_32x32x16_bf16 v[16:31], v[180:183], v[160:163], v[16:31]
	ds_read_b128 v[176:179], v200 offset:8704
	v_exp_f32_e32 v3, v139
	v_add_f32_e32 v11, v0, v1
	v_cvt_pk_bf16_f32 v164, v0, v1
	v_add_f32_e32 v11, v11, v2
	s_waitcnt lgkmcnt(2)
	v_mfma_f32_32x32x16_bf16 v[64:79], v[222:225], v[120:123], v[64:79]
	ds_read_b64_tr_b16 v[180:181], v201 offset:44032
	ds_read_b64_tr_b16 v[182:183], v201 offset:45568
	v_add_f32_e32 v11, v11, v3
	v_cvt_pk_bf16_f32 v165, v2, v3
	v_exp_f32_e32 v6, v140
	v_exp_f32_e32 v7, v141
	s_waitcnt lgkmcnt(3)
	v_mfma_f32_32x32x16_bf16 v[64:79], v[226:229], v[124:127], v[64:79]
	ds_read_b64_tr_b16 v[222:223], v201 offset:44096
	ds_read_b64_tr_b16 v[224:225], v201 offset:45632
	v_exp_f32_e32 v8, v142
	v_exp_f32_e32 v9, v143
	v_add_f32_e32 v11, v11, v6
	v_add_f32_e32 v11, v11, v7
	s_waitcnt lgkmcnt(4)
	v_mfma_f32_32x32x16_bf16 v[80:95], v[176:179], v[104:107], v[48:63]
	ds_read_b128 v[226:229], v200 offset:8736
	v_cvt_pk_bf16_f32 v166, v6, v7
	v_add_f32_e32 v11, v11, v8
	v_add_f32_e32 v11, v11, v9
	v_cvt_pk_bf16_f32 v167, v8, v9
	s_waitcnt lgkmcnt(3)
	s_nop 0
	v_mfma_f32_32x32x16_bf16 v[32:47], v[180:183], v[164:167], v[32:47]
	ds_read_b128 v[176:179], v200 offset:8768
	v_exp_f32_e32 v0, v144
	v_exp_f32_e32 v1, v145
	v_exp_f32_e32 v2, v146
	s_waitcnt lgkmcnt(2)
	v_mfma_f32_32x32x16_bf16 v[16:31], v[222:225], v[164:167], v[16:31]
	ds_read_b128 v[180:183], v200 offset:8800
	v_exp_f32_e32 v3, v147
	v_add_f32_e32 v12, v0, v1
	v_cvt_pk_bf16_f32 v168, v0, v1
	v_add_f32_e32 v12, v12, v2
	s_waitcnt lgkmcnt(2)
	v_mfma_f32_32x32x16_bf16 v[80:95], v[226:229], v[108:111], v[80:95]
	ds_read_b64_tr_b16 v[222:223], v201 offset:47104
	ds_read_b64_tr_b16 v[224:225], v201 offset:48640
	v_add_f32_e32 v12, v12, v3
	v_cvt_pk_bf16_f32 v169, v2, v3
	v_exp_f32_e32 v6, v148
	v_exp_f32_e32 v7, v149
	s_waitcnt lgkmcnt(3)
	v_mfma_f32_32x32x16_bf16 v[80:95], v[176:179], v[112:115], v[80:95]
	ds_read_b64_tr_b16 v[226:227], v201 offset:47168
	ds_read_b64_tr_b16 v[228:229], v201 offset:48704
	v_exp_f32_e32 v8, v150
	v_exp_f32_e32 v9, v151
	v_add_f32_e32 v12, v12, v6
	v_add_f32_e32 v12, v12, v7
	s_waitcnt lgkmcnt(4)
	v_mfma_f32_32x32x16_bf16 v[80:95], v[180:183], v[116:119], v[80:95]
	ds_read_b128 v[176:179], v200 offset:8832
	v_cvt_pk_bf16_f32 v170, v6, v7
	v_add_f32_e32 v12, v12, v8
	v_add_f32_e32 v12, v12, v9
	v_cvt_pk_bf16_f32 v171, v8, v9
	s_waitcnt lgkmcnt(3)
	s_nop 0
	v_mfma_f32_32x32x16_bf16 v[32:47], v[222:225], v[168:171], v[32:47]
	ds_read_b128 v[180:183], v200 offset:8864
	v_exp_f32_e32 v0, v152
	v_exp_f32_e32 v1, v153
	v_exp_f32_e32 v2, v154
	v_exp_f32_e32 v3, v155
	s_waitcnt lgkmcnt(2)
	v_mfma_f32_32x32x16_bf16 v[16:31], v[226:229], v[168:171], v[16:31]
	ds_read_b64_tr_b16 v[222:223], v201 offset:50176
	ds_read_b64_tr_b16 v[224:225], v201 offset:51712
	v_add_f32_e32 v13, v0, v1
	v_cvt_pk_bf16_f32 v172, v0, v1
	v_add_f32_e32 v13, v13, v2
	v_add_f32_e32 v13, v13, v3
	v_cvt_pk_bf16_f32 v173, v2, v3
	s_waitcnt lgkmcnt(3)
	v_mfma_f32_32x32x16_bf16 v[80:95], v[176:179], v[120:123], v[80:95]
	ds_read_b64_tr_b16 v[226:227], v201 offset:50240
	ds_read_b64_tr_b16 v[228:229], v201 offset:51776
	v_exp_f32_e32 v6, v156
	v_exp_f32_e32 v7, v157
	v_exp_f32_e32 v8, v158
	v_exp_f32_e32 v9, v159
	v_add_f32_e32 v13, v13, v6
	s_waitcnt lgkmcnt(4)
	v_mfma_f32_32x32x16_bf16 v[80:95], v[180:183], v[124:127], v[80:95]
	v_add_f32_e32 v13, v13, v7
	v_cvt_pk_bf16_f32 v174, v6, v7
	v_add_f32_e32 v13, v13, v8
	v_add_f32_e32 v13, v13, v9
	v_cvt_pk_bf16_f32 v175, v8, v9
	s_waitcnt lgkmcnt(2)
	s_nop 0
	v_mfma_f32_32x32x16_bf16 v[32:47], v[222:225], v[172:175], v[32:47]
	s_waitcnt lgkmcnt(0)
	v_mfma_f32_32x32x16_bf16 v[16:31], v[226:229], v[172:175], v[16:31]
	v_add_f32_e32 v10, v10, v11
	v_add_f32_e32 v12, v12, v13
	v_add_f32_e32 v10, v10, v12
	v_add_f32_e32 v192, v192, v10
	v_max_f32_e32 v193, v193, v10
	s_add_u32 s28, s28, 2
	s_cmpk_lt_u32 s28, 0x80
	s_waitcnt lgkmcnt(0)
	s_cbranch_scc1 .Lmla_loop
; DI unsigned pk2(float lo, float hi) { f32x2 v = {lo, hi}; b16x2 r = __builtin_convertvector(v, b16x2); return __builtin_bit_cast(unsigned, r); }
; DI float bflo(unsigned w) { return __uint_as_float(w << 16); }
; DI float bfhi(unsigned w) { return __uint_as_float(w & 0xffff0000u); }
; template <int MODE>
; DI void attn_item(const Params& p, int layer, int bh, int qb, char* lds) {
;     ...
;   __syncthreads();
;   const size_t trow = (size_t)b * S + q0w + l32;
;   const u16* grow = (const u16*)(p.ws + OFF_H) + trow * DIN + C_GATE + ocol;
;   u16* orow = (u16*)(p.ws + OFF_OB) + trow * DM + ocol;
;   float inv0 = 1.f / xchg_sum(l[0]);
;   if (MODE == 1) {
;     const float* lm = (const float*)(p.ws + OFF_LAM);
;     const float lam = lm[layer], post = lm[4 + layer];
;     const float inv1 = lam / xchg_sum(l[1]);
;     float ss = 0.f;
; #pragma unroll
;     for (int dt = 0; dt < 2; ++dt)
; #pragma unroll
;       for (int r = 0; r < 16; ++r) { float v = O[0][dt][r] * inv0 - O[NMAP - 1][dt][r] * inv1; O[0][dt][r] = v; ss += v * v; }
;     ss = xchg_sum(ss);
;     inv0 = rsqrtf(ss * (1.f / 64.f) + 1e-6f) * post;
;   }
; #pragma unroll
;   for (int dt = 0; dt < 2; ++dt)
; #pragma unroll
;     for (int g = 0; g < 4; ++g) {
;       const int d = 32 * dt + 8 * g + 4 * hh;
;       u32x2 gw = *(const u32x2*)(grow + d);
;       float v0 = O[0][dt][4 * g + 0] * inv0, v1 = O[0][dt][4 * g + 1] * inv0, v2 = O[0][dt][4 * g + 2] * inv0, v3 = O[0][dt][4 * g + 3] * inv0;
;       if (MODE == 1) { const float* sl = p.subln + layer * 64 + d; v0 *= sl[0]; v1 *= sl[1]; v2 *= sl[2]; v3 *= sl[3]; }
;       v0 *= bflo(gw[0]); v1 *= bfhi(gw[0]); v2 *= bflo(gw[1]); v3 *= bfhi(gw[1]);
;       u32x2 ow = {pk2(v0, v1), pk2(v2, v3)};
;     ...
;       if (MODE == PROBE_ZERO_MODE) { ow[0] = 0u; ow[1] = 0u; }
;     ...
;       *(u32x2*)(orow + d) = ow;
;     }
	s_barrier
	s_waitcnt vmcnt(0)
	s_lshl_b64 s[6:7], s[10:11], 13
	v_ashrrev_i32_e32 v187, 31, v186
	v_lshl_add_u64 v[0:1], s[6:7], 0, v[186:187]
	v_or_b32_e32 v0, v0, v204
	v_mov_b32_e32 v2, s34
	v_mov_b32_e32 v3, s35
	v_mad_u64_u32 v[2:3], s[6:7], v0, s64, v[2:3]
	v_mad_i32_i24 v3, v1, s64, v3
	s_lshl_b32 s4, s52, 7
	v_lshl_add_u32 v12, v206, 1, s4
	v_mov_b32_e32 v13, 0
	v_lshl_add_u64 v[6:7], v[2:3], 0, v[12:13]
	s_mov_b64 s[6:7], 0x6058ec0
	v_lshl_add_u64 v[6:7], v[6:7], 0, s[6:7]
	global_load_dwordx2 v[64:65], v[6:7], off offset:0
	global_load_dwordx2 v[66:67], v[6:7], off offset:16
	global_load_dwordx2 v[68:69], v[6:7], off offset:32
	global_load_dwordx2 v[70:71], v[6:7], off offset:48
	global_load_dwordx2 v[72:73], v[6:7], off offset:64
	global_load_dwordx2 v[74:75], v[6:7], off offset:80
	global_load_dwordx2 v[76:77], v[6:7], off offset:96
	global_load_dwordx2 v[78:79], v[6:7], off offset:112
	v_readlane_b32 s6, v254, 49
	v_readlane_b32 s7, v254, 50
	v_lshlrev_b64 v[0:1], 11, v[0:1]
	s_nop 0
	v_lshl_add_u64 v[0:1], s[6:7], 0, v[0:1]
	v_lshl_add_u64 v[8:9], v[0:1], 0, v[12:13]
	v_cmp_nge_f32_e32 vcc, s94, v193
	s_nop 0
	s_cmp_lg_u64 vcc, 0
	s_cselect_b32 s24, 1, 0
	v_mov_b32_e32 v196, s24
	v_lshrrev_b32_e32 v197, 6, v184
	v_lshlrev_b32_e32 v197, 2, v197
	ds_write_b32 v197, v196 offset:0
	s_waitcnt lgkmcnt(0)
	s_barrier
	v_mov_b32_e32 v197, 0
	ds_read_b128 v[176:179], v197 offset:0
	ds_read_b128 v[180:183], v197 offset:16
	v_mov_b32_e32 v2, v192
	s_nop 1
	v_permlane32_swap_b32_e32 v192, v2
	v_add_f32_e32 v2, v192, v2
	v_div_scale_f32 v3, s[4:5], v2, v2, 1.0
	v_rcp_f32_e32 v4, v3
	s_nop 0
	v_fma_f32 v10, -v3, v4, 1.0
	v_fmac_f32_e32 v4, v10, v4
	v_div_scale_f32 v10, vcc, 1.0, v2, 1.0
	v_mul_f32_e32 v11, v10, v4
	v_fma_f32 v12, -v3, v11, v10
	v_fmac_f32_e32 v11, v12, v4
	v_fma_f32 v3, -v3, v11, v10
	s_nop 1
	v_div_fmas_f32 v3, v3, v4, v11
	v_div_fixup_f32 v2, v3, v2, 1.0
	s_waitcnt lgkmcnt(0)
	v_or3_b32 v196, v176, v177, v178
	v_or3_b32 v196, v196, v179, v180
	v_or3_b32 v196, v196, v181, v182
	v_or_b32_e32 v196, v196, v183
	s_nop 0
	v_readfirstlane_b32 s24, v196
	s_barrier
	s_cmp_lg_u32 s24, 0
	s_cbranch_scc1 .Lmla_slow
	s_waitcnt vmcnt(0)
	v_mul_f32_e32 v32, v32, v2
	v_mul_f32_e32 v33, v33, v2
	v_mul_f32_e32 v34, v34, v2
	v_mul_f32_e32 v35, v35, v2
	v_lshlrev_b32_e32 v196, 16, v64
	v_and_b32_e32 v197, 0xffff0000, v64
	v_mul_f32_e32 v32, v32, v196
	v_mul_f32_e32 v33, v33, v197
	v_lshlrev_b32_e32 v196, 16, v65
	v_and_b32_e32 v197, 0xffff0000, v65
	v_mul_f32_e32 v34, v34, v196
	v_mul_f32_e32 v35, v35, v197
	v_cvt_pk_bf16_f32 v32, v32, v33
	v_cvt_pk_bf16_f32 v33, v34, v35
	global_store_dwordx2 v[8:9], v[32:33], off offset:0
	v_mul_f32_e32 v36, v36, v2
	v_mul_f32_e32 v37, v37, v2
	v_mul_f32_e32 v38, v38, v2
	v_mul_f32_e32 v39, v39, v2
	v_lshlrev_b32_e32 v196, 16, v66
	v_and_b32_e32 v197, 0xffff0000, v66
	v_mul_f32_e32 v36, v36, v196
	v_mul_f32_e32 v37, v37, v197
	v_lshlrev_b32_e32 v196, 16, v67
	v_and_b32_e32 v197, 0xffff0000, v67
	v_mul_f32_e32 v38, v38, v196
	v_mul_f32_e32 v39, v39, v197
	v_cvt_pk_bf16_f32 v36, v36, v37
	v_cvt_pk_bf16_f32 v37, v38, v39
	global_store_dwordx2 v[8:9], v[36:37], off offset:16
	v_mul_f32_e32 v40, v40, v2
	v_mul_f32_e32 v41, v41, v2
	v_mul_f32_e32 v42, v42, v2
	v_mul_f32_e32 v43, v43, v2
	v_lshlrev_b32_e32 v196, 16, v68
	v_and_b32_e32 v197, 0xffff0000, v68
	v_mul_f32_e32 v40, v40, v196
	v_mul_f32_e32 v41, v41, v197
	v_lshlrev_b32_e32 v196, 16, v69
	v_and_b32_e32 v197, 0xffff0000, v69
	v_mul_f32_e32 v42, v42, v196
	v_mul_f32_e32 v43, v43, v197
	v_cvt_pk_bf16_f32 v40, v40, v41
	v_cvt_pk_bf16_f32 v41, v42, v43
	global_store_dwordx2 v[8:9], v[40:41], off offset:32
	v_mul_f32_e32 v44, v44, v2
	v_mul_f32_e32 v45, v45, v2
	v_mul_f32_e32 v46, v46, v2
	v_mul_f32_e32 v47, v47, v2
	v_lshlrev_b32_e32 v196, 16, v70
	v_and_b32_e32 v197, 0xffff0000, v70
	v_mul_f32_e32 v44, v44, v196
	v_mul_f32_e32 v45, v45, v197
	v_lshlrev_b32_e32 v196, 16, v71
	v_and_b32_e32 v197, 0xffff0000, v71
	v_mul_f32_e32 v46, v46, v196
	v_mul_f32_e32 v47, v47, v197
	v_cvt_pk_bf16_f32 v44, v44, v45
	v_cvt_pk_bf16_f32 v45, v46, v47
	global_store_dwordx2 v[8:9], v[44:45], off offset:48
	v_mul_f32_e32 v16, v16, v2
	v_mul_f32_e32 v17, v17, v2
	v_mul_f32_e32 v18, v18, v2
	v_mul_f32_e32 v19, v19, v2
	v_lshlrev_b32_e32 v196, 16, v72
	v_and_b32_e32 v197, 0xffff0000, v72
	v_mul_f32_e32 v16, v16, v196
	v_mul_f32_e32 v17, v17, v197
	v_lshlrev_b32_e32 v196, 16, v73
	v_and_b32_e32 v197, 0xffff0000, v73
	v_mul_f32_e32 v18, v18, v196
	v_mul_f32_e32 v19, v19, v197
	v_cvt_pk_bf16_f32 v16, v16, v17
	v_cvt_pk_bf16_f32 v17, v18, v19
	global_store_dwordx2 v[8:9], v[16:17], off offset:64
	v_mul_f32_e32 v20, v20, v2
	v_mul_f32_e32 v21, v21, v2
	v_mul_f32_e32 v22, v22, v2
	v_mul_f32_e32 v23, v23, v2
	v_lshlrev_b32_e32 v196, 16, v74
	v_and_b32_e32 v197, 0xffff0000, v74
	v_mul_f32_e32 v20, v20, v196
	v_mul_f32_e32 v21, v21, v197
	v_lshlrev_b32_e32 v196, 16, v75
	v_and_b32_e32 v197, 0xffff0000, v75
	v_mul_f32_e32 v22, v22, v196
	v_mul_f32_e32 v23, v23, v197
	v_cvt_pk_bf16_f32 v20, v20, v21
	v_cvt_pk_bf16_f32 v21, v22, v23
	global_store_dwordx2 v[8:9], v[20:21], off offset:80
	v_mul_f32_e32 v24, v24, v2
	v_mul_f32_e32 v25, v25, v2
	v_mul_f32_e32 v26, v26, v2
	v_mul_f32_e32 v27, v27, v2
	v_lshlrev_b32_e32 v196, 16, v76
	v_and_b32_e32 v197, 0xffff0000, v76
	v_mul_f32_e32 v24, v24, v196
	v_mul_f32_e32 v25, v25, v197
	v_lshlrev_b32_e32 v196, 16, v77
	v_and_b32_e32 v197, 0xffff0000, v77
	v_mul_f32_e32 v26, v26, v196
	v_mul_f32_e32 v27, v27, v197
	v_cvt_pk_bf16_f32 v24, v24, v25
	v_cvt_pk_bf16_f32 v25, v26, v27
	global_store_dwordx2 v[8:9], v[24:25], off offset:96
	v_mul_f32_e32 v28, v28, v2
	v_mul_f32_e32 v29, v29, v2
	v_mul_f32_e32 v30, v30, v2
	v_mul_f32_e32 v31, v31, v2
	v_lshlrev_b32_e32 v196, 16, v78
	v_and_b32_e32 v197, 0xffff0000, v78
	v_mul_f32_e32 v28, v28, v196
	v_mul_f32_e32 v29, v29, v197
	v_lshlrev_b32_e32 v196, 16, v79
	v_and_b32_e32 v197, 0xffff0000, v79
	v_mul_f32_e32 v30, v30, v196
	v_mul_f32_e32 v31, v31, v197
	v_cvt_pk_bf16_f32 v28, v28, v29
	v_cvt_pk_bf16_f32 v29, v30, v31
	global_store_dwordx2 v[8:9], v[28:29], off offset:112
	s_branch .LBB0_321
